# g2 chunk epilogue: branch-free fast path for full chunks (4 independent chains per row group)
# speedup vs baseline: 1.0161x; 1.0078x over previous
; #define LAS __attribute__((address_space(3)))
; __device__ __forceinline__ unsigned f2bf(float f) { const f32x2_ v = {f, 0.f}; const bf16x2_ b = __builtin_convertvector(v, bf16x2_); return __builtin_bit_cast(unsigned, b) & 0xffffu; }
; __device__ __forceinline__ float siluf_(float x) { return x * sigmoidf_(x); }
; __device__ __forceinline__ void g2_phase(const PP P, int l, LAS unsigned char* lds) {
;     ...
;             if (act) {
; #pragma unroll
;                 for (int mi = 0; mi < 4; ++mi)
; #pragma unroll
;                     for (int j = 0; j < 4; ++j) { const int i = 16 * mi + fq * 4 + j; LAS float* rp = red + (n & 1) * 256 + i;
;                         const float tot = rp[0] + rp[64] + rp[128] + rp[192]; const float rinv = __builtin_amdgcn_rsqf(tot * (1.0f / 64.0f) + 1e-6f);
;                         if (i < L) { const size_t row = seq0 + (size_t)n * 64 + i;
;                             MIX[row * 1024 + 512 + h * 64 + dv] = (bf16)f2bf(O[mi][j] * rinv * gnw * siluf_(zr[mi][j])); } }
;             }
.LBB0_162:
	s_or_b64 exec, exec, s[56:57]
	s_waitcnt lgkmcnt(0)
	s_barrier
	s_and_saveexec_b64 s[56:57], s[6:7]
	s_cbranch_execz .LBB0_120
	s_cmp_lt_i32 s66, 64
	s_cbranch_scc0 .Lg2e_slow
	v_lshl_add_u32 v24, s71, 10, v125
	ds_read_b128 v[178:181], v24
	ds_read_b128 v[182:185], v24 offset:256
	ds_read_b128 v[186:189], v24 offset:512
	ds_read_b128 v[190:193], v24 offset:768
	ds_read_b128 v[196:199], v24 offset:64
	ds_read_b128 v[200:203], v24 offset:320
	ds_read_b128 v[204:207], v24 offset:576
	ds_read_b128 v[208:211], v24 offset:832
	ds_read_b128 v[212:215], v24 offset:128
	ds_read_b128 v[216:219], v24 offset:384
	ds_read_b128 v[220:223], v24 offset:640
	ds_read_b128 v[224:227], v24 offset:896
	v_lshl_add_u64 v[158:159], s[48:49], 0, v[26:27]
	s_mov_b32 s58, 0x7160c00
	s_mov_b32 s59, 0
	v_lshl_add_u64 v[158:159], v[158:159], 0, s[58:59]
	s_mov_b64 s[58:59], 0x1000
	v_lshl_add_u64 v[162:163], v[158:159], 0, s[58:59]
	s_waitcnt vmcnt(0)
	v_mul_f32_e32 v244, 0xbfb8aa3b, v93
	v_mul_f32_e32 v245, 0xbfb8aa3b, v92
	v_mul_f32_e32 v246, 0xbfb8aa3b, v95
	v_mul_f32_e32 v247, 0xbfb8aa3b, v94
	v_exp_f32_e32 v244, v244
	v_exp_f32_e32 v245, v245
	v_exp_f32_e32 v246, v246
	v_exp_f32_e32 v247, v247
	v_add_f32_e32 v244, 1.0, v244
	v_add_f32_e32 v245, 1.0, v245
	v_add_f32_e32 v246, 1.0, v246
	v_add_f32_e32 v247, 1.0, v247
	v_rcp_f32_e32 v244, v244
	v_rcp_f32_e32 v245, v245
	v_rcp_f32_e32 v246, v246
	v_rcp_f32_e32 v247, v247
	s_waitcnt lgkmcnt(8)
	v_add_f32_e32 v248, v178, v182
	v_add_f32_e32 v249, v179, v183
	v_add_f32_e32 v250, v180, v184
	v_add_f32_e32 v251, v181, v185
	v_add_f32_e32 v248, v248, v186
	v_add_f32_e32 v249, v249, v187
	v_add_f32_e32 v250, v250, v188
	v_add_f32_e32 v251, v251, v189
	v_add_f32_e32 v248, v248, v190
	v_add_f32_e32 v249, v249, v191
	v_add_f32_e32 v250, v250, v192
	v_add_f32_e32 v251, v251, v193
	ds_read_b128 v[228:231], v24 offset:192
	ds_read_b128 v[232:235], v24 offset:448
	ds_read_b128 v[236:239], v24 offset:704
	ds_read_b128 v[240:243], v24 offset:960
	v_fmamk_f32 v248, v248, 0x3c800000, v165
	v_fmamk_f32 v249, v249, 0x3c800000, v165
	v_fmamk_f32 v250, v250, 0x3c800000, v165
	v_fmamk_f32 v251, v251, 0x3c800000, v165
	v_rsq_f32_e32 v248, v248
	v_rsq_f32_e32 v249, v249
	v_rsq_f32_e32 v250, v250
	v_rsq_f32_e32 v251, v251
	v_mul_f32_e32 v244, v93, v244
	v_mul_f32_e32 v245, v92, v245
	v_mul_f32_e32 v246, v95, v246
	v_mul_f32_e32 v247, v94, v247
	v_mul_f32_e32 v248, v16, v248
	v_mul_f32_e32 v249, v17, v249
	v_mul_f32_e32 v250, v18, v250
	v_mul_f32_e32 v251, v19, v251
	v_mul_f32_e32 v248, v149, v248
	v_mul_f32_e32 v249, v149, v249
	v_mul_f32_e32 v250, v149, v250
	v_mul_f32_e32 v251, v149, v251
	v_mul_f32_e32 v248, v244, v248
	v_mul_f32_e32 v249, v245, v249
	v_mul_f32_e32 v250, v246, v250
	v_mul_f32_e32 v251, v247, v251
	v_cvt_pk_bf16_f32 v248, v248, s0
	v_cvt_pk_bf16_f32 v249, v249, s0
	v_cvt_pk_bf16_f32 v250, v250, s0
	v_cvt_pk_bf16_f32 v251, v251, s0
	global_store_short v[158:159], v248, off
	global_store_short v[158:159], v249, off offset:2048
	global_store_short v[162:163], v250, off
	global_store_short v[162:163], v251, off offset:2048
	s_mov_b64 s[58:59], 0x8000
	v_lshl_add_u64 v[158:159], v[158:159], 0, s[58:59]
	v_lshl_add_u64 v[162:163], v[162:163], 0, s[58:59]
	v_mul_f32_e32 v244, 0xbfb8aa3b, v96
	v_mul_f32_e32 v245, 0xbfb8aa3b, v97
	v_mul_f32_e32 v246, 0xbfb8aa3b, v98
	v_mul_f32_e32 v247, 0xbfb8aa3b, v99
	v_exp_f32_e32 v244, v244
	v_exp_f32_e32 v245, v245
	v_exp_f32_e32 v246, v246
	v_exp_f32_e32 v247, v247
	v_add_f32_e32 v244, 1.0, v244
	v_add_f32_e32 v245, 1.0, v245
	v_add_f32_e32 v246, 1.0, v246
	v_add_f32_e32 v247, 1.0, v247
	v_rcp_f32_e32 v244, v244
	v_rcp_f32_e32 v245, v245
	v_rcp_f32_e32 v246, v246
	v_rcp_f32_e32 v247, v247
	s_waitcnt lgkmcnt(8)
	v_add_f32_e32 v248, v196, v200
	v_add_f32_e32 v249, v197, v201
	v_add_f32_e32 v250, v198, v202
	v_add_f32_e32 v251, v199, v203
	v_add_f32_e32 v248, v248, v204
	v_add_f32_e32 v249, v249, v205
	v_add_f32_e32 v250, v250, v206
	v_add_f32_e32 v251, v251, v207
	v_add_f32_e32 v248, v248, v208
	v_add_f32_e32 v249, v249, v209
	v_add_f32_e32 v250, v250, v210
	v_add_f32_e32 v251, v251, v211
	v_fmamk_f32 v248, v248, 0x3c800000, v165
	v_fmamk_f32 v249, v249, 0x3c800000, v165
	v_fmamk_f32 v250, v250, 0x3c800000, v165
	v_fmamk_f32 v251, v251, 0x3c800000, v165
	v_rsq_f32_e32 v248, v248
	v_rsq_f32_e32 v249, v249
	v_rsq_f32_e32 v250, v250
	v_rsq_f32_e32 v251, v251
	v_mul_f32_e32 v244, v96, v244
	v_mul_f32_e32 v245, v97, v245
	v_mul_f32_e32 v246, v98, v246
	v_mul_f32_e32 v247, v99, v247
	v_mul_f32_e32 v248, v20, v248
	v_mul_f32_e32 v249, v21, v249
	v_mul_f32_e32 v250, v22, v250
	v_mul_f32_e32 v251, v23, v251
	v_mul_f32_e32 v248, v149, v248
	v_mul_f32_e32 v249, v149, v249
	v_mul_f32_e32 v250, v149, v250
	v_mul_f32_e32 v251, v149, v251
	v_mul_f32_e32 v248, v244, v248
	v_mul_f32_e32 v249, v245, v249
	v_mul_f32_e32 v250, v246, v250
	v_mul_f32_e32 v251, v247, v251
	v_cvt_pk_bf16_f32 v248, v248, s0
	v_cvt_pk_bf16_f32 v249, v249, s0
	v_cvt_pk_bf16_f32 v250, v250, s0
	v_cvt_pk_bf16_f32 v251, v251, s0
	global_store_short v[158:159], v248, off
	global_store_short v[158:159], v249, off offset:2048
	global_store_short v[162:163], v250, off
	global_store_short v[162:163], v251, off offset:2048
	s_mov_b64 s[58:59], 0x8000
	v_lshl_add_u64 v[158:159], v[158:159], 0, s[58:59]
	v_lshl_add_u64 v[162:163], v[162:163], 0, s[58:59]
	v_mul_f32_e32 v244, 0xbfb8aa3b, v100
	v_mul_f32_e32 v245, 0xbfb8aa3b, v101
	v_mul_f32_e32 v246, 0xbfb8aa3b, v102
	v_mul_f32_e32 v247, 0xbfb8aa3b, v103
	v_exp_f32_e32 v244, v244
	v_exp_f32_e32 v245, v245
	v_exp_f32_e32 v246, v246
	v_exp_f32_e32 v247, v247
	v_add_f32_e32 v244, 1.0, v244
	v_add_f32_e32 v245, 1.0, v245
	v_add_f32_e32 v246, 1.0, v246
	v_add_f32_e32 v247, 1.0, v247
	v_rcp_f32_e32 v244, v244
	v_rcp_f32_e32 v245, v245
	v_rcp_f32_e32 v246, v246
	v_rcp_f32_e32 v247, v247
	s_waitcnt lgkmcnt(4)
; #define LAS __attribute__((address_space(3)))
; __device__ __forceinline__ unsigned f2bf(float f) { const f32x2_ v = {f, 0.f}; const bf16x2_ b = __builtin_convertvector(v, bf16x2_); return __builtin_bit_cast(unsigned, b) & 0xffffu; }
; __device__ __forceinline__ float siluf_(float x) { return x * sigmoidf_(x); }
; __device__ __forceinline__ void g2_phase(const PP P, int l, LAS unsigned char* lds) {
;     ...
;             if (act) {
; #pragma unroll
;                 for (int mi = 0; mi < 4; ++mi)
; #pragma unroll
;                     for (int j = 0; j < 4; ++j) { const int i = 16 * mi + fq * 4 + j; LAS float* rp = red + (n & 1) * 256 + i;
;                         const float tot = rp[0] + rp[64] + rp[128] + rp[192]; const float rinv = __builtin_amdgcn_rsqf(tot * (1.0f / 64.0f) + 1e-6f);
;                         if (i < L) { const size_t row = seq0 + (size_t)n * 64 + i;
;                             MIX[row * 1024 + 512 + h * 64 + dv] = (bf16)f2bf(O[mi][j] * rinv * gnw * siluf_(zr[mi][j])); } }
;             }
	v_add_f32_e32 v248, v212, v216
	v_add_f32_e32 v249, v213, v217
	v_add_f32_e32 v250, v214, v218
	v_add_f32_e32 v251, v215, v219
	v_add_f32_e32 v248, v248, v220
	v_add_f32_e32 v249, v249, v221
	v_add_f32_e32 v250, v250, v222
	v_add_f32_e32 v251, v251, v223
	v_add_f32_e32 v248, v248, v224
	v_add_f32_e32 v249, v249, v225
	v_add_f32_e32 v250, v250, v226
	v_add_f32_e32 v251, v251, v227
	v_fmamk_f32 v248, v248, 0x3c800000, v165
	v_fmamk_f32 v249, v249, 0x3c800000, v165
	v_fmamk_f32 v250, v250, 0x3c800000, v165
	v_fmamk_f32 v251, v251, 0x3c800000, v165
	v_rsq_f32_e32 v248, v248
	v_rsq_f32_e32 v249, v249
	v_rsq_f32_e32 v250, v250
	v_rsq_f32_e32 v251, v251
	v_mul_f32_e32 v244, v100, v244
	v_mul_f32_e32 v245, v101, v245
	v_mul_f32_e32 v246, v102, v246
	v_mul_f32_e32 v247, v103, v247
	v_mul_f32_e32 v248, v28, v248
	v_mul_f32_e32 v249, v29, v249
	v_mul_f32_e32 v250, v30, v250
	v_mul_f32_e32 v251, v31, v251
	v_mul_f32_e32 v248, v149, v248
	v_mul_f32_e32 v249, v149, v249
	v_mul_f32_e32 v250, v149, v250
	v_mul_f32_e32 v251, v149, v251
	v_mul_f32_e32 v248, v244, v248
	v_mul_f32_e32 v249, v245, v249
	v_mul_f32_e32 v250, v246, v250
	v_mul_f32_e32 v251, v247, v251
	v_cvt_pk_bf16_f32 v248, v248, s0
	v_cvt_pk_bf16_f32 v249, v249, s0
	v_cvt_pk_bf16_f32 v250, v250, s0
	v_cvt_pk_bf16_f32 v251, v251, s0
	global_store_short v[158:159], v248, off
	global_store_short v[158:159], v249, off offset:2048
	global_store_short v[162:163], v250, off
	global_store_short v[162:163], v251, off offset:2048
	s_mov_b64 s[58:59], 0x8000
	v_lshl_add_u64 v[158:159], v[158:159], 0, s[58:59]
	v_lshl_add_u64 v[162:163], v[162:163], 0, s[58:59]
	v_mul_f32_e32 v244, 0xbfb8aa3b, v154
	v_mul_f32_e32 v245, 0xbfb8aa3b, v155
	v_mul_f32_e32 v246, 0xbfb8aa3b, v156
	v_mul_f32_e32 v247, 0xbfb8aa3b, v157
	v_exp_f32_e32 v244, v244
	v_exp_f32_e32 v245, v245
	v_exp_f32_e32 v246, v246
	v_exp_f32_e32 v247, v247
	v_add_f32_e32 v244, 1.0, v244
	v_add_f32_e32 v245, 1.0, v245
	v_add_f32_e32 v246, 1.0, v246
	v_add_f32_e32 v247, 1.0, v247
	v_rcp_f32_e32 v244, v244
	v_rcp_f32_e32 v245, v245
	v_rcp_f32_e32 v246, v246
	v_rcp_f32_e32 v247, v247
	s_waitcnt lgkmcnt(0)
	v_add_f32_e32 v248, v228, v232
	v_add_f32_e32 v249, v229, v233
	v_add_f32_e32 v250, v230, v234
	v_add_f32_e32 v251, v231, v235
	v_add_f32_e32 v248, v248, v236
	v_add_f32_e32 v249, v249, v237
	v_add_f32_e32 v250, v250, v238
	v_add_f32_e32 v251, v251, v239
	v_add_f32_e32 v248, v248, v240
	v_add_f32_e32 v249, v249, v241
	v_add_f32_e32 v250, v250, v242
	v_add_f32_e32 v251, v251, v243
	v_fmamk_f32 v248, v248, 0x3c800000, v165
	v_fmamk_f32 v249, v249, 0x3c800000, v165
	v_fmamk_f32 v250, v250, 0x3c800000, v165
	v_fmamk_f32 v251, v251, 0x3c800000, v165
	v_rsq_f32_e32 v248, v248
	v_rsq_f32_e32 v249, v249
	v_rsq_f32_e32 v250, v250
	v_rsq_f32_e32 v251, v251
	v_mul_f32_e32 v244, v154, v244
	v_mul_f32_e32 v245, v155, v245
	v_mul_f32_e32 v246, v156, v246
	v_mul_f32_e32 v247, v157, v247
	v_mul_f32_e32 v248, v36, v248
	v_mul_f32_e32 v249, v37, v249
	v_mul_f32_e32 v250, v38, v250
	v_mul_f32_e32 v251, v39, v251
	v_mul_f32_e32 v248, v149, v248
	v_mul_f32_e32 v249, v149, v249
	v_mul_f32_e32 v250, v149, v250
	v_mul_f32_e32 v251, v149, v251
	v_mul_f32_e32 v248, v244, v248
	v_mul_f32_e32 v249, v245, v249
	v_mul_f32_e32 v250, v246, v250
	v_mul_f32_e32 v251, v247, v251
	v_cvt_pk_bf16_f32 v248, v248, s0
	v_cvt_pk_bf16_f32 v249, v249, s0
	v_cvt_pk_bf16_f32 v250, v250, s0
	v_cvt_pk_bf16_f32 v251, v251, s0
	global_store_short v[158:159], v248, off
	global_store_short v[158:159], v249, off offset:2048
	global_store_short v[162:163], v250, off
	global_store_short v[162:163], v251, off offset:2048
	s_branch .LBB0_120
; #define LAS __attribute__((address_space(3)))
; __device__ __forceinline__ unsigned f2bf(float f) { const f32x2_ v = {f, 0.f}; const bf16x2_ b = __builtin_convertvector(v, bf16x2_); return __builtin_bit_cast(unsigned, b) & 0xffffu; }
; __device__ __forceinline__ float siluf_(float x) { return x * sigmoidf_(x); }
; __device__ __forceinline__ void g2_phase(const PP P, int l, LAS unsigned char* lds) {
;     ...
;             if (act) {
; #pragma unroll
;                 for (int mi = 0; mi < 4; ++mi)
; #pragma unroll
;                     for (int j = 0; j < 4; ++j) { const int i = 16 * mi + fq * 4 + j; LAS float* rp = red + (n & 1) * 256 + i;
;                         const float tot = rp[0] + rp[64] + rp[128] + rp[192]; const float rinv = __builtin_amdgcn_rsqf(tot * (1.0f / 64.0f) + 1e-6f);
;                         if (i < L) { const size_t row = seq0 + (size_t)n * 64 + i;
;                             MIX[row * 1024 + 512 + h * 64 + dv] = (bf16)f2bf(O[mi][j] * rinv * gnw * siluf_(zr[mi][j])); } }
;             }
.Lg2e_slow:
	v_lshl_add_u32 v24, s71, 10, v125
	ds_read_b128 v[178:181], v24
	ds_read_b128 v[182:185], v24 offset:256
	ds_read_b128 v[186:189], v24 offset:512
	ds_read_b128 v[190:193], v24 offset:768
	v_mul_f32_e32 v158, 0xbfb8aa3b, v93
	v_exp_f32_e32 v158, v158
	s_waitcnt lgkmcnt(2)
	v_add_f32_e32 v148, v178, v182
	s_waitcnt lgkmcnt(1)
	v_add_f32_e32 v148, v148, v186
	s_waitcnt lgkmcnt(0)
	ds_read_b128 v[196:199], v24 offset:64
	ds_read_b128 v[200:203], v24 offset:320
	ds_read_b128 v[204:207], v24 offset:576
	ds_read_b128 v[208:211], v24 offset:832
	ds_read_b128 v[212:215], v24 offset:128
	ds_read_b128 v[216:219], v24 offset:384
	ds_read_b128 v[220:223], v24 offset:640
	ds_read_b128 v[224:227], v24 offset:896
	ds_read_b128 v[228:231], v24 offset:192
	ds_read_b128 v[232:235], v24 offset:448
	ds_read_b128 v[236:239], v24 offset:704
	ds_read_b128 v[240:243], v24 offset:960
	v_add_f32_e32 v148, v148, v190
	v_fmamk_f32 v148, v148, 0x3c800000, v165
	v_rsq_f32_e32 v148, v148
	v_add_f32_e32 v158, 1.0, v158
	v_rcp_f32_e32 v158, v158
	s_mov_b32 s58, 0x7160000
	v_mul_f32_e32 v148, v16, v148
	s_waitcnt vmcnt(0)
	v_mul_f32_e32 v148, v149, v148
	v_mul_f32_e32 v158, v93, v158
	v_mul_f32_e32 v148, v158, v148
	v_lshl_add_u64 v[158:159], s[48:49], 0, v[26:27]
	v_add_co_u32_e32 v162, vcc, s58, v158
	v_cvt_pk_bf16_f32 v148, v148, s0
	s_nop 0
	v_addc_co_u32_e32 v163, vcc, 0, v159, vcc
	v_mul_f32_e32 v161, 0xbfb8aa3b, v92
	global_store_short v[162:163], v148, off offset:3072
	v_add_f32_e32 v148, v179, v183
	v_exp_f32_e32 v161, v161
	v_add_f32_e32 v148, v148, v187
	v_add_f32_e32 v148, v148, v191
	v_fmamk_f32 v148, v148, 0x3c800000, v165
	v_rsq_f32_e32 v148, v148
	v_add_f32_e32 v161, 1.0, v161
	v_rcp_f32_e32 v161, v161
	s_mov_b32 s58, 0x7161000
	v_mul_f32_e32 v148, v17, v148
	v_mul_f32_e32 v148, v149, v148
	v_mul_f32_e32 v161, v92, v161
	v_mul_f32_e32 v148, v161, v148
	v_add_co_u32_e32 v162, vcc, s58, v158
	v_cvt_pk_bf16_f32 v148, v148, s0
	s_nop 0
	v_addc_co_u32_e32 v163, vcc, 0, v159, vcc
	v_mul_f32_e32 v161, 0xbfb8aa3b, v95
	global_store_short v[162:163], v148, off offset:1024
	v_add_f32_e32 v148, v180, v184
	v_exp_f32_e32 v161, v161
	v_add_f32_e32 v148, v148, v188
	v_add_f32_e32 v148, v148, v192
	v_fmamk_f32 v148, v148, 0x3c800000, v165
	v_rsq_f32_e32 v148, v148
	v_add_f32_e32 v161, 1.0, v161
	v_rcp_f32_e32 v161, v161
	v_mul_f32_e32 v148, v18, v148
	v_mul_f32_e32 v148, v149, v148
	v_mul_f32_e32 v161, v95, v161
	v_mul_f32_e32 v148, v161, v148
	v_cvt_pk_bf16_f32 v148, v148, s0
	v_mul_f32_e32 v161, 0xbfb8aa3b, v94
	global_store_short v[162:163], v148, off offset:3072
	v_add_f32_e32 v148, v181, v185
	v_exp_f32_e32 v161, v161
	v_add_f32_e32 v148, v148, v189
	v_add_f32_e32 v148, v148, v193
	v_fmamk_f32 v148, v148, 0x3c800000, v165
	v_rsq_f32_e32 v148, v148
	v_add_f32_e32 v161, 1.0, v161
	v_rcp_f32_e32 v161, v161
	v_add_co_u32_e32 v162, vcc, 0x7162000, v158
	v_mul_f32_e32 v148, v19, v148
	v_mul_f32_e32 v148, v149, v148
	v_mul_f32_e32 v161, v94, v161
	v_mul_f32_e32 v148, v161, v148
	v_cvt_pk_bf16_f32 v148, v148, s0
	v_addc_co_u32_e32 v163, vcc, 0, v159, vcc
	global_store_short v[162:163], v148, off offset:1024
	s_waitcnt lgkmcnt(0)
	s_and_saveexec_b64 s[58:59], s[22:23]
	s_cbranch_execz .LBB0_175
	v_mov_b32_e32 v162, v196
	v_mov_b32_e32 v163, v200
	s_waitcnt lgkmcnt(0)
	v_add_f32_e32 v148, v162, v163
	v_mov_b32_e32 v162, v204
	v_mov_b32_e32 v163, v208
	s_waitcnt lgkmcnt(0)
	v_add_f32_e32 v148, v148, v162
	v_add_f32_e32 v148, v148, v163
	v_fmamk_f32 v148, v148, 0x3c800000, v165
	v_rsq_f32_e32 v148, v148
	s_nop 0
	v_mul_f32_e32 v163, v20, v148
	v_mul_f32_e32 v148, 0xbfb8aa3b, v96
	v_exp_f32_e32 v148, v148
	s_nop 0
	v_add_f32_e32 v148, 1.0, v148
	v_rcp_f32_e32 v162, v148
	v_mov_b32_e32 v148, v96
	v_pk_mul_f32 v[162:163], v[148:149], v[162:163]
	s_nop 0
	v_mul_f32_e32 v148, v162, v163
	v_add_co_u32_e32 v162, vcc, 0x7168000, v158
	v_cvt_pk_bf16_f32 v148, v148, s0
	s_nop 0
	v_addc_co_u32_e32 v163, vcc, 0, v159, vcc
	global_store_short v[162:163], v148, off offset:3072
	s_or_b64 exec, exec, s[58:59]
	s_and_saveexec_b64 s[58:59], s[24:25]
	s_cbranch_execnz .LBB0_176
